# attention units: nt hint on the once-read Q fragment loads and gate-row loads (K/V tiles unchanged), on top of the nt ninth-round conversion stream
# speedup vs baseline: 1.0015x; 1.0015x over previous
.LBB0_762:
	s_andn2_b64 vcc, exec, s[8:9]
	s_cbranch_vccnz .LBB0_804
	s_bfe_u32 s0, s95, 0x10005
	s_ashr_i32 s10, s95, 6
	s_and_b32 s78, s95, 31
	s_lshl_b32 s6, s0, 2
	v_readlane_b32 s7, v254, 34
	s_or_b32 s8, s6, s7
	s_lshl_b32 s79, s10, 12
	s_lshl_b32 s6, s78, 7
	s_or_b32 s11, s6, s79
	v_readlane_b32 s13, v254, 38
	s_add_i32 s82, s11, s13
	s_lshl_b32 s57, s8, 6
	s_lshl_b32 s6, s8, 7
	s_add_u32 s6, s70, s6
	s_addc_u32 s7, s71, 0
	v_and_b32_e32 v32, 48, v207
	s_lshl_b32 s5, s5, 3
	v_and_b32_e32 v201, 15, v206
	v_lshl_add_u64 v[2:3], s[6:7], 0, v[32:33]
	s_or_b32 s6, s8, s5
	v_or_b32_e32 v0, s82, v201
	s_ashr_i32 s7, s6, 31
	v_ashrrev_i32_e32 v1, 31, v0
	s_lshl_b64 s[6:7], s[6:7], 2
	v_lshlrev_b64 v[4:5], 13, v[0:1]
	s_add_u32 s6, s36, s6
	s_addc_u32 s7, s37, s7
	v_lshl_add_u64 v[4:5], v[2:3], 0, v[4:5]
	global_load_dword v6, v33, s[6:7]
	global_load_dwordx4 v[72:75], v[4:5], off nt
	global_load_dwordx4 v[76:79], v[4:5], off offset:64 nt
	v_or_b32_e32 v4, 16, v0
	v_ashrrev_i32_e32 v5, 31, v4
	s_add_i32 s5, s78, -1
	v_lshlrev_b64 v[4:5], 13, v[4:5]
	s_cmp_gt_u32 s5, 31
	v_lshl_add_u64 v[4:5], v[2:3], 0, v[4:5]
	s_cselect_b64 s[6:7], -1, 0
	s_lshl_b32 s8, s5, 7
	global_load_dwordx4 v[84:87], v[4:5], off nt
	global_load_dwordx4 v[88:91], v[4:5], off offset:64 nt
	v_or_b32_e32 v4, 32, v0
	v_or_b32_e32 v0, 48, v0
	s_add_i32 s12, s8, s79
	v_ashrrev_i32_e32 v5, 31, v4
	v_ashrrev_i32_e32 v1, 31, v0
	s_cmp_lt_u32 s5, 32
	v_lshlrev_b64 v[4:5], 13, v[4:5]
	v_lshlrev_b64 v[0:1], 13, v[0:1]
	s_cselect_b64 s[8:9], -1, 0
	v_lshl_add_u64 v[4:5], v[2:3], 0, v[4:5]
	v_lshl_add_u64 v[0:1], v[2:3], 0, v[0:1]
	v_cndmask_b32_e64 v3, 0, 1, s[8:9]
	s_and_b64 s[8:9], s[8:9], exec
	global_load_dwordx4 v[100:103], v[4:5], off nt
	global_load_dwordx4 v[104:107], v[4:5], off offset:64 nt
	global_load_dwordx4 v[108:111], v[0:1], off nt
	global_load_dwordx4 v[112:115], v[0:1], off offset:64 nt
	v_ashrrev_i32_e32 v205, 3, v206
	s_cselect_b32 s5, s12, s11
	s_lshl_b32 s0, s0, 7
	v_lshlrev_b32_e32 v1, 3, v206
	v_add_u32_e32 v0, s5, v205
	s_add_u32 s8, s70, s0
	v_and_b32_e32 v2, 56, v1
	s_addc_u32 s9, s71, 0
	v_lshlrev_b32_e32 v32, 1, v2
	v_ashrrev_i32_e32 v1, 31, v0
	v_lshl_add_u64 v[202:203], s[8:9], 0, v[32:33]
	v_lshlrev_b64 v[0:1], 13, v[0:1]
	v_lshl_add_u64 v[0:1], v[202:203], 0, v[0:1]
	s_mov_b64 s[8:9], 0x80000
	global_load_dwordx4 v[120:123], v[0:1], off offset:1024
	global_load_dwordx4 v[124:127], v[0:1], off offset:1280
	v_lshl_add_u64 v[0:1], v[0:1], 0, s[8:9]
	global_load_dwordx4 v[128:131], v[0:1], off offset:1024
	global_load_dwordx4 v[132:135], v[0:1], off offset:1280
	v_lshrrev_b32_e32 v0, 4, v207
	s_movk_i32 s0, 0x48
	v_and_b32_e32 v5, -8, v206
	v_lshlrev_b32_e32 v204, 3, v0
	v_lshlrev_b32_e32 v7, 2, v0
	v_mad_u64_u32 v[0:1], s[8:9], v205, s0, v[2:3]
	v_lshlrev_b32_e32 v209, 1, v0
	v_cndmask_b32_e64 v1, 0, 1, s[6:7]
	v_add_lshl_u32 v211, v0, v5, 1
	v_add_u32_e32 v0, 0x1200, v0
	v_readfirstlane_b32 s16, v1
	v_lshlrev_b32_e32 v212, 1, v0
	v_add_u32_e32 v0, v5, v0
	v_mov_b32_e32 v1, 0x400
	v_lshl_add_u32 v213, v0, 1, v1
	v_add_u32_e32 v0, s13, v201
	v_bfe_u32 v4, v206, 2, 2
	v_sub_u32_e32 v214, v0, v7
	v_and_b32_e32 v0, 3, v206
	v_readlane_b32 s6, v254, 15
	v_mov_b32_e32 v37, v36
	v_mov_b32_e32 v38, v36
	v_mov_b32_e32 v39, v36
	v_mov_b32_e32 v32, v33
	v_mov_b32_e32 v34, v33
	v_mov_b32_e32 v35, v33
	v_readfirstlane_b32 s0, v3
	s_lshl_b32 s5, s10, 8
	v_lshl_add_u32 v215, v0, 3, s6
	v_or_b32_e32 v243, v4, v7
	v_mov_b64_e32 v[0:1], v[32:33]
	v_mov_b64_e32 v[20:21], v[32:33]
	v_mov_b64_e32 v[50:51], v[34:35]
	v_mov_b64_e32 v[70:71], v[34:35]
	v_mov_b64_e32 v[8:9], v[32:33]
	v_mov_b64_e32 v[42:43], v[34:35]
	s_waitcnt vmcnt(12)
	v_mul_f32_e32 v210, 0x3fb8aa3b, v6
	v_mov_b64_e32 v[62:63], v[34:35]
	v_mov_b64_e32 v[98:99], v[34:35]
	v_mov_b64_e32 v[16:17], v[36:37]
	v_mov_b64_e32 v[46:47], v[38:39]
	v_mov_b64_e32 v[66:67], v[38:39]
	v_mov_b64_e32 v[118:119], v[38:39]
	v_mov_b64_e32 v[94:95], v[34:35]
	v_mov_b64_e32 v[58:59], v[34:35]
	v_mov_b64_e32 v[28:29], v[32:33]
	v_mov_b64_e32 v[12:13], v[32:33]
	v_mov_b64_e32 v[82:83], v[34:35]
	v_mov_b64_e32 v[54:55], v[34:35]
	v_mov_b64_e32 v[24:25], v[32:33]
	v_mov_b64_e32 v[4:5], v[32:33]
	v_and_b32_e32 v208, 48, v206
	s_addk_i32 s5, 0x3e80
	s_mov_b32 s83, s78
	s_mov_b32 s92, s78
	s_mov_b32 s95, s78
	s_mov_b32 s96, s78
	s_mov_b32 s97, s78
	s_mov_b32 s64, s78
	s_mov_b32 s81, s78
	s_mov_b32 s90, 0
	v_mov_b64_e32 v[2:3], v[34:35]
	v_mov_b64_e32 v[22:23], v[34:35]
	v_mov_b64_e32 v[48:49], v[32:33]
	v_mov_b64_e32 v[68:69], v[32:33]
	v_mov_b64_e32 v[10:11], v[34:35]
	v_mov_b64_e32 v[40:41], v[32:33]
	v_mov_b64_e32 v[60:61], v[32:33]
	v_mov_b64_e32 v[96:97], v[32:33]
	v_mov_b32_e32 v244, v210
	v_mov_b32_e32 v245, v210
	v_mov_b32_e32 v246, v210
	v_xor_b32_e32 v228, 0x80000000, v210
	v_mov_b32_e32 v229, v228
	v_mov_b32_e32 v230, v228
	v_mov_b32_e32 v231, v228
	v_mov_b32_e32 v232, v228
	v_mov_b32_e32 v233, v228
	v_mov_b32_e32 v234, v228
	v_mov_b32_e32 v235, v228
	v_mov_b32_e32 v248, v228
	v_mov_b32_e32 v249, v228
	v_mov_b32_e32 v250, v228
	v_mov_b32_e32 v251, v228
	v_mov_b32_e32 v220, v228
	v_mov_b32_e32 v221, v228
	v_mov_b32_e32 v222, v228
	v_mov_b32_e32 v223, v228
	v_mov_b64_e32 v[18:19], v[38:39]
	v_mov_b64_e32 v[44:45], v[36:37]
	v_mov_b64_e32 v[64:65], v[36:37]
	v_mov_b64_e32 v[116:117], v[36:37]
	v_mov_b64_e32 v[92:93], v[32:33]
	v_mov_b64_e32 v[56:57], v[32:33]
	v_mov_b64_e32 v[30:31], v[34:35]
	v_mov_b64_e32 v[14:15], v[34:35]
	v_mov_b64_e32 v[80:81], v[32:33]
	v_mov_b64_e32 v[52:53], v[32:33]
	v_mov_b64_e32 v[26:27], v[34:35]
	v_mov_b64_e32 v[6:7], v[34:35]
	s_barrier
